# combination: seam1 + P0 w_up transpose (8 loads in flight, 1 KB-contiguous write deal) + nt hint on single-use P0 source loads
# speedup vs baseline: 1.0076x; 1.0036x over previous
.LBB0_19:
	s_andn2_b64 vcc, exec, s[4:5]
	s_cbranch_vccnz .LBB0_38
	s_add_i32 s0, s28, 0xa000
	s_lshr_b32 s0, s0, 3
	s_and_b32 s17, s0, 0xe00
	s_and_b32 s0, s28, 7
	s_lshl_b32 s0, s0, 6
	s_or_b32 s17, s17, s0
	s_lshl_b32 s16, s28, 2
	s_and_b32 s16, s16, 0x3fe0
	s_lshl_b32 s0, s16, 2
	v_or_b32_e32 v6, s17, v1
	v_lshl_add_u64 v[40:41], v[18:19], 0, s[0:1]
	v_lshlrev_b32_e32 v14, 16, v6
	v_add_lshl_u32 v39, s17, v1, 2
	v_lshl_add_u64 v[4:5], v[40:41], 0, v[14:15]
	global_load_dwordx4 v[4:7], v[4:5], off nt
	v_or_b32_sdwa v14, s17, v17 dst_sel:WORD_1 dst_unused:UNUSED_PAD src0_sel:DWORD src1_sel:DWORD
	s_nop 0
	v_lshl_add_u64 v[8:9], v[40:41], 0, v[14:15]
	global_load_dwordx4 v[8:11], v[8:9], off nt
	v_or_b32_sdwa v14, s17, v42 dst_sel:WORD_1 dst_unused:UNUSED_PAD src0_sel:DWORD src1_sel:DWORD
	s_nop 0
	v_lshl_add_u64 v[60:61], v[40:41], 0, v[14:15]
	global_load_dwordx4 v[60:63], v[60:61], off nt
	v_or_b32_sdwa v14, s17, v43 dst_sel:WORD_1 dst_unused:UNUSED_PAD src0_sel:DWORD src1_sel:DWORD
	s_nop 0
	v_lshl_add_u64 v[64:65], v[40:41], 0, v[14:15]
	global_load_dwordx4 v[64:67], v[64:65], off nt
	v_or_b32_sdwa v14, s17, v44 dst_sel:WORD_1 dst_unused:UNUSED_PAD src0_sel:DWORD src1_sel:DWORD
	s_nop 0
	v_lshl_add_u64 v[68:69], v[40:41], 0, v[14:15]
	global_load_dwordx4 v[68:71], v[68:69], off nt
	v_or_b32_sdwa v14, s17, v45 dst_sel:WORD_1 dst_unused:UNUSED_PAD src0_sel:DWORD src1_sel:DWORD
	s_nop 0
	v_lshl_add_u64 v[72:73], v[40:41], 0, v[14:15]
	global_load_dwordx4 v[72:75], v[72:73], off nt
	v_or_b32_sdwa v14, s17, v46 dst_sel:WORD_1 dst_unused:UNUSED_PAD src0_sel:DWORD src1_sel:DWORD
	s_nop 0
	v_lshl_add_u64 v[76:77], v[40:41], 0, v[14:15]
	global_load_dwordx4 v[76:79], v[76:77], off nt
	v_or_b32_sdwa v14, s17, v47 dst_sel:WORD_1 dst_unused:UNUSED_PAD src0_sel:DWORD src1_sel:DWORD
	s_nop 0
	v_lshl_add_u64 v[80:81], v[40:41], 0, v[14:15]
	global_load_dwordx4 v[80:83], v[80:81], off nt
	s_and_b64 vcc, exec, s[12:13]
	s_cbranch_vccz .Lwup_noscale
	v_readlane_b32 s46, v249, 30
	v_readlane_b32 s47, v249, 31
	v_readlane_b32 s36, v249, 20
	v_readlane_b32 s37, v249, 21
	v_readlane_b32 s38, v249, 22
	v_readlane_b32 s39, v249, 23
	v_readlane_b32 s40, v249, 24
	v_readlane_b32 s41, v249, 25
	v_readlane_b32 s42, v249, 26
	v_readlane_b32 s43, v249, 27
	v_readlane_b32 s44, v249, 28
	v_readlane_b32 s45, v249, 29
	v_readlane_b32 s48, v249, 32
	v_readlane_b32 s49, v249, 33
	v_readlane_b32 s50, v249, 34
	v_readlane_b32 s51, v249, 35
	global_load_dword v2, v39, s[46:47]
	s_nop 0
	global_load_dword v3, v39, s[46:47] offset:32
	s_nop 0
	global_load_dword v12, v39, s[46:47] offset:64
	s_nop 0
	global_load_dword v13, v39, s[46:47] offset:96
	s_nop 0
	global_load_dword v14, v39, s[46:47] offset:128
	s_nop 0
	global_load_dword v40, v39, s[46:47] offset:160
	s_nop 0
	global_load_dword v41, v39, s[46:47] offset:192
	s_nop 0
	global_load_dword v39, v39, s[46:47] offset:224
	s_waitcnt vmcnt(0)
	v_mul_f32_e32 v4, v2, v4
	v_mul_f32_e32 v5, v2, v5
	v_mul_f32_e32 v6, v2, v6
	v_mul_f32_e32 v7, v2, v7
	v_mul_f32_e32 v8, v3, v8
	v_mul_f32_e32 v9, v3, v9
	v_mul_f32_e32 v10, v3, v10
	v_mul_f32_e32 v11, v3, v11
	v_mul_f32_e32 v60, v12, v60
	v_mul_f32_e32 v61, v12, v61
	v_mul_f32_e32 v62, v12, v62
	v_mul_f32_e32 v63, v12, v63
	v_mul_f32_e32 v64, v13, v64
	v_mul_f32_e32 v65, v13, v65
	v_mul_f32_e32 v66, v13, v66
	v_mul_f32_e32 v67, v13, v67
	v_mul_f32_e32 v68, v14, v68
	v_mul_f32_e32 v69, v14, v69
	v_mul_f32_e32 v70, v14, v70
	v_mul_f32_e32 v71, v14, v71
	v_mul_f32_e32 v72, v40, v72
	v_mul_f32_e32 v73, v40, v73
	v_mul_f32_e32 v74, v40, v74
	v_mul_f32_e32 v75, v40, v75
	v_mul_f32_e32 v76, v41, v76
	v_mul_f32_e32 v77, v41, v77
	v_mul_f32_e32 v78, v41, v78
	v_mul_f32_e32 v79, v41, v79
	v_mul_f32_e32 v80, v39, v80
	v_mul_f32_e32 v81, v39, v81
	v_mul_f32_e32 v82, v39, v82
	v_mul_f32_e32 v83, v39, v83

.LBB0_42:
	s_andn2_b64 vcc, exec, s[4:5]
	s_cbranch_vccnz .LBB0_10
	s_ashr_i32 s0, s28, 31
	s_lshr_b32 s0, s0, 24
	s_add_i32 s0, s28, s0
	s_ashr_i32 s0, s0, 8
	s_lshl_b32 s16, s0, 6
	s_lshl_b32 s0, s0, 13
	s_sub_i32 s4, s9, s0
	v_or_b32_e32 v2, s16, v1
	v_or_b32_e32 v4, s16, v17
	v_or_b32_e32 v10, s16, v42
	v_or_b32_e32 v12, s16, v43
	v_or_b32_e32 v64, s16, v44
	v_or_b32_e32 v66, s16, v45
	s_ashr_i32 s5, s4, 31
	v_ashrrev_i32_e32 v3, 31, v2
	v_ashrrev_i32_e32 v5, 31, v4
	v_ashrrev_i32_e32 v11, 31, v10
	v_ashrrev_i32_e32 v13, 31, v12
	v_ashrrev_i32_e32 v65, 31, v64
	v_ashrrev_i32_e32 v67, 31, v66
	v_lshl_add_u64 v[40:41], s[4:5], 2, v[26:27]
	v_lshlrev_b64 v[2:3], 15, v[2:3]
	v_lshlrev_b64 v[4:5], 15, v[4:5]
	v_lshlrev_b64 v[10:11], 15, v[10:11]
	v_lshlrev_b64 v[12:13], 15, v[12:13]
	v_lshlrev_b64 v[64:65], 15, v[64:65]
	v_lshlrev_b64 v[66:67], 15, v[66:67]
	v_lshl_add_u64 v[2:3], v[40:41], 0, v[2:3]
	v_lshl_add_u64 v[6:7], v[40:41], 0, v[4:5]
	v_lshl_add_u64 v[10:11], v[40:41], 0, v[10:11]
	v_lshl_add_u64 v[60:61], v[40:41], 0, v[12:13]
	v_lshl_add_u64 v[64:65], v[40:41], 0, v[64:65]
	v_lshl_add_u64 v[68:69], v[40:41], 0, v[66:67]
	global_load_dwordx4 v[2:5], v[2:3], off nt
	s_nop 0
	global_load_dwordx4 v[6:9], v[6:7], off nt
	s_nop 0
	global_load_dwordx4 v[10:13], v[10:11], off nt
	s_nop 0
	global_load_dwordx4 v[60:63], v[60:61], off nt
	s_nop 0
	global_load_dwordx4 v[64:67], v[64:65], off nt
	s_nop 0
	global_load_dwordx4 v[68:71], v[68:69], off nt
	v_or_b32_e32 v72, s16, v46
	v_ashrrev_i32_e32 v73, 31, v72
	v_lshlrev_b64 v[72:73], 15, v[72:73]
	v_or_b32_e32 v76, s16, v47
	v_lshl_add_u64 v[72:73], v[40:41], 0, v[72:73]
	v_ashrrev_i32_e32 v77, 31, v76
	global_load_dwordx4 v[72:75], v[72:73], off nt
	v_lshlrev_b64 v[76:77], 15, v[76:77]
	v_lshl_add_u64 v[40:41], v[40:41], 0, v[76:77]
	global_load_dwordx4 v[76:79], v[40:41], off nt
	v_add_u32_e32 v14, 0x18c0, v49
	v_add_u32_e32 v39, 0x18c8, v49
	v_add_u32_e32 v40, 0x1ce0, v49
	v_add_u32_e32 v41, 0x1ce8, v49
	s_ashr_i32 s17, s16, 31
	s_waitcnt vmcnt(7)
	ds_write2_b32 v49, v2, v3 offset1:1
	ds_write2_b32 v49, v4, v5 offset0:2 offset1:3
	s_waitcnt vmcnt(6)
	ds_write2_b32 v50, v6, v7 offset1:1
	ds_write2_b32 v51, v8, v9 offset1:1
	s_waitcnt vmcnt(5)
	ds_write2_b32 v52, v10, v11 offset1:1
	ds_write2_b32 v53, v12, v13 offset1:1
	s_waitcnt vmcnt(4)
	ds_write2_b32 v54, v60, v61 offset1:1
	ds_write2_b32 v55, v62, v63 offset1:1
	s_waitcnt vmcnt(3)
	ds_write2_b32 v56, v64, v65 offset1:1
	ds_write2_b32 v57, v66, v67 offset1:1
	s_waitcnt vmcnt(2)
	ds_write2_b32 v58, v68, v69 offset1:1
	ds_write2_b32 v59, v70, v71 offset1:1
	s_waitcnt vmcnt(1)
	ds_write2_b32 v14, v72, v73 offset1:1
	ds_write2_b32 v39, v74, v75 offset1:1
	s_waitcnt vmcnt(0)
	ds_write2_b32 v40, v76, v77 offset1:1
	ds_write2_b32 v41, v78, v79 offset1:1
	s_waitcnt lgkmcnt(0)
	v_add_u32_e32 v10, s4, v1
	ds_read2_b32 v[2:3], v48 offset1:33
	v_ashrrev_i32_e32 v11, 31, v10
	s_waitcnt lgkmcnt(0)
	v_cvt_pk_bf16_f32 v2, v2, v3
	ds_read2_b32 v[4:5], v48 offset0:66 offset1:99
	v_lshl_add_u64 v[8:9], s[16:17], 1, v[28:29]
	v_lshlrev_b64 v[12:13], 13, v[10:11]
	s_waitcnt lgkmcnt(0)
	v_cvt_pk_bf16_f32 v3, v4, v5
	ds_read2_b32 v[4:5], v48 offset0:132 offset1:165
	v_lshl_add_u64 v[12:13], v[8:9], 0, v[12:13]
	s_waitcnt lgkmcnt(0)
	v_cvt_pk_bf16_f32 v4, v4, v5
	ds_read2_b32 v[6:7], v48 offset0:198 offset1:231
	s_waitcnt lgkmcnt(0)
	v_cvt_pk_bf16_f32 v5, v6, v7
	global_store_dwordx4 v[12:13], v[2:5], off
	v_add_u32_e32 v12, 8, v10
	v_ashrrev_i32_e32 v13, 31, v12
	ds_read2_b32 v[6:7], v48 offset0:8 offset1:41
	s_waitcnt lgkmcnt(0)
	v_cvt_pk_bf16_f32 v2, v6, v7
	ds_read2_b32 v[4:5], v48 offset0:74 offset1:107
	v_lshlrev_b64 v[12:13], 13, v[12:13]
	s_waitcnt lgkmcnt(0)
	v_cvt_pk_bf16_f32 v3, v4, v5
	ds_read2_b32 v[4:5], v48 offset0:140 offset1:173
	v_lshl_add_u64 v[12:13], v[8:9], 0, v[12:13]
	s_waitcnt lgkmcnt(0)
	v_cvt_pk_bf16_f32 v4, v4, v5
	ds_read2_b32 v[6:7], v48 offset0:206 offset1:239
	s_waitcnt lgkmcnt(0)
	v_cvt_pk_bf16_f32 v5, v6, v7
	global_store_dwordx4 v[12:13], v[2:5], off
	v_add_u32_e32 v12, 16, v10
	ds_read2_b32 v[6:7], v48 offset0:16 offset1:49
	s_waitcnt lgkmcnt(0)
	v_cvt_pk_bf16_f32 v2, v6, v7
	ds_read2_b32 v[4:5], v48 offset0:82 offset1:115
	v_ashrrev_i32_e32 v13, 31, v12
	s_waitcnt lgkmcnt(0)
	v_cvt_pk_bf16_f32 v3, v4, v5
	ds_read2_b32 v[4:5], v48 offset0:148 offset1:181
	v_lshlrev_b64 v[12:13], 13, v[12:13]
	s_waitcnt lgkmcnt(0)
	v_cvt_pk_bf16_f32 v4, v4, v5
	ds_read2_b32 v[6:7], v48 offset0:214 offset1:247
	s_waitcnt lgkmcnt(0)
	v_cvt_pk_bf16_f32 v5, v6, v7
	v_lshl_add_u64 v[12:13], v[8:9], 0, v[12:13]
	ds_read2_b32 v[6:7], v48 offset0:24 offset1:57
	global_store_dwordx4 v[12:13], v[2:5], off
	v_add_u32_e32 v10, 24, v10
	v_ashrrev_i32_e32 v11, 31, v10
	s_waitcnt lgkmcnt(0)
	v_cvt_pk_bf16_f32 v2, v6, v7
	ds_read2_b32 v[4:5], v48 offset0:90 offset1:123
	s_waitcnt lgkmcnt(0)
	v_cvt_pk_bf16_f32 v3, v4, v5
	ds_read2_b32 v[4:5], v48 offset0:156 offset1:189
	s_waitcnt lgkmcnt(0)
	v_cvt_pk_bf16_f32 v4, v4, v5
	ds_read2_b32 v[6:7], v48 offset0:222 offset1:255
	v_lshlrev_b64 v[10:11], 13, v[10:11]
	s_waitcnt lgkmcnt(0)
	v_cvt_pk_bf16_f32 v5, v6, v7
	v_lshl_add_u64 v[6:7], v[8:9], 0, v[10:11]
	global_store_dwordx4 v[6:7], v[2:5], off
	s_waitcnt lgkmcnt(0)
	s_branch .LBB0_10
.LBB0_45:
	s_cmpk_gt_i32 s8, 0x47ff
	v_mov_b32_e32 v67, 0
	s_cbranch_scc1 .LBB0_50
	v_mbcnt_lo_u32_b32 v1, -1, 0
	v_mbcnt_hi_u32_b32 v2, -1, v1
	v_and_b32_e32 v1, 64, v2
	v_add_u32_e32 v3, 64, v1
	v_xor_b32_e32 v1, 1, v2
	v_cmp_lt_i32_e32 vcc, v1, v3
	v_xor_b32_e32 v4, 2, v2
	v_lshlrev_b32_e32 v66, 3, v196
	v_cndmask_b32_e32 v1, v2, v1, vcc
	v_cmp_lt_i32_e32 vcc, v4, v3
	v_lshl_add_u64 v[68:69], s[86:87], 0, v[66:67]
	v_lshlrev_b32_e32 v66, 4, v196
	v_cndmask_b32_e32 v4, v2, v4, vcc
	v_lshlrev_b32_e32 v96, 2, v4
	v_xor_b32_e32 v4, 4, v2
	v_cmp_lt_i32_e32 vcc, v4, v3
	v_lshl_add_u64 v[70:71], s[64:65], 0, v[66:67]
	s_mov_b64 s[0:1], 0x1000
	v_cndmask_b32_e32 v4, v2, v4, vcc
	v_lshl_add_u64 v[72:73], v[70:71], 0, s[0:1]
	s_mov_b64 s[0:1], 0x1400
	v_lshlrev_b32_e32 v97, 2, v4
	v_xor_b32_e32 v4, 8, v2
	v_lshl_add_u64 v[74:75], v[70:71], 0, s[0:1]
	s_mov_b64 s[0:1], 0x1800
	v_cmp_lt_i32_e32 vcc, v4, v3
	v_lshl_add_u64 v[76:77], v[70:71], 0, s[0:1]
	s_mov_b64 s[0:1], 0x1c00
	v_cndmask_b32_e32 v4, v2, v4, vcc
	v_lshl_add_u64 v[78:79], v[70:71], 0, s[0:1]
	s_mov_b64 s[0:1], 0x2000
	v_lshlrev_b32_e32 v98, 2, v4
	v_xor_b32_e32 v4, 16, v2
	v_lshl_add_u64 v[80:81], v[70:71], 0, s[0:1]
	s_mov_b64 s[0:1], 0x2400
	v_cmp_lt_i32_e32 vcc, v4, v3
	v_lshl_add_u64 v[82:83], v[70:71], 0, s[0:1]
	s_mov_b64 s[0:1], 0x2800
	v_cndmask_b32_e32 v4, v2, v4, vcc
	v_lshl_add_u64 v[84:85], v[70:71], 0, s[0:1]
	s_mov_b64 s[0:1], 0x2c00
	v_lshlrev_b32_e32 v99, 2, v4
	v_xor_b32_e32 v4, 32, v2
	v_lshl_add_u64 v[86:87], v[70:71], 0, s[0:1]
	s_mov_b64 s[0:1], 0x3000
	v_cmp_lt_i32_e32 vcc, v4, v3
	v_lshl_add_u64 v[88:89], v[70:71], 0, s[0:1]
	s_mov_b64 s[0:1], 0x3400
	v_cndmask_b32_e32 v2, v2, v4, vcc
	v_lshl_add_u64 v[90:91], v[70:71], 0, s[0:1]
	s_mov_b64 s[0:1], 0x3800
	s_ashr_i32 s9, s8, 31
	v_lshlrev_b32_e32 v100, 2, v2
	v_lshl_add_u64 v[92:93], v[70:71], 0, s[0:1]
	v_mov_b32_e32 v2, 0x3c00
	s_ashr_i32 s11, s10, 31
	s_lshl_b64 s[0:1], s[8:9], 14
	v_lshl_or_b32 v2, v0, 4, v2
	v_mov_b32_e32 v3, v67
	s_add_u32 s12, s52, s0
	s_mov_b32 s5, 0
	v_lshlrev_b32_e32 v1, 2, v1
	v_lshl_add_u64 v[94:95], s[64:65], 0, v[2:3]
	s_addc_u32 s13, s53, s1
	s_lshl_b64 s[14:15], s[10:11], 14
	s_movk_i32 s20, 0x1000
	s_movk_i32 s21, 0x2000
	s_movk_i32 s28, 0x3000
	v_mov_b32_e32 v101, 0x358637bd
	s_mov_b32 s29, 0xf800000
	v_mov_b32_e32 v102, 0x260
	s_mov_b64 s[16:17], s[8:9]
	s_branch .LBB0_48
